# DN loop: final iteration skips the useless wrap-around LDS-DMA prefetch loads when there is no next unit (adjusted vmcnt waits)
# baseline (speedup 1.0000x reference)
; #define PG8_STAGE(bufoff, gbase, voff) do { _Pragma("unroll") for (int _i = 0; _i < 2; ++_i) \
;         __builtin_amdgcn_global_load_lds((const unsigned*)((const char*)(gbase) + (voff)[_i]), (PG8_LAS unsigned*)(lds + (bufoff) + ldsw + _i * 8192), 16, 0, 0); } while (0)
; #define PG8_LDA(dst, b, h) do { _Pragma("unroll") for (int m = 0; m < 4; ++m) _Pragma("unroll") for (int k = 0; k < 2; ++k) dst[m][k] = *(const PG8_LAS bf16x8*)(lds + PG8_SA(b, h) + aoff + m * 2048 + k * 1024); } while (0)
; #define PG8_LDB(dst, b, h) do { _Pragma("unroll") for (int n = 0; n < 2; ++n) _Pragma("unroll") for (int k = 0; k < 2; ++k) dst[n][k] = *(const PG8_LAS bf16x8*)(lds + PG8_SB(b, h) + boff + n * 2048 + k * 1024); } while (0)
; #define PG8_MMA(ai, bj, At, Bt) do { __builtin_amdgcn_s_setprio(1); _Pragma("unroll") for (int m = 0; m < 4; ++m) _Pragma("unroll") for (int n = 0; n < 2; ++n) _Pragma("unroll") for (int k = 0; k < 2; ++k) \
;         acc[ai][bj][m][n] = __builtin_amdgcn_mfma_f32_16x16x32_bf16(Bt[n][k], At[m][k], acc[ai][bj][m][n], 0, 0, 0); __builtin_amdgcn_s_setprio(0); } while (0)
; #define PG8_WAIT_V(n) asm volatile("s_waitcnt vmcnt(" #n ")" ::: "memory")
; #define PG8_WAIT_L(n) asm volatile("s_waitcnt lgkmcnt(" #n ")" ::: "memory")
; #define PG8_BAR __builtin_amdgcn_s_barrier()
; #define PG8_SCHED __builtin_amdgcn_sched_barrier(0)
; template <class Epi, class Sched, bool ALIGN_EPI = false, bool SP2 = false>
; __device__ __forceinline__ void gemm_phase(PG8_LAS unsigned char* lds, const Gemm g, const Sched& S, const Epi& E) {
;     ...
;         for (int t = 0; t < nt; t += 2) {
;             const bool last = (t == nt - 2);
;             const char* a1 = cA + (size_t)(t + 1) * kstep;
;             const char* a2 = last ? nA : cA + (size_t)(t + 2) * kstep; const char* b2 = last ? nB : cB + (size_t)(t + 2) * kstep;
;             const char* a3 = a2 + kstep; const char* b3 = b2 + kstep;
;             if (last && has_next) S.a_ready(nxt);
;             if constexpr (SP2) {
;             PG8_LDB(B0, 0, 0); PG8_LDB(B1, 0, 1); PG8_SCHED; PG8_LDA(At, 0, 0); PG8_STAGE(PG8_SA(1, 1), a1 + hstep, voffA);
;             PG8_WAIT_V(8); PG8_WAIT_L(0); PG8_BAR; PG8_MMA(0, 0, At, B0); PG8_MMA(0, 1, At, B1); PG8_BAR; PG8_SCHED;
;             PG8_LDA(At, 0, 1); PG8_STAGE(PG8_SB(0, 0), b2, voffB); PG8_STAGE(PG8_SB(0, 1), b2 + hstep, voffB); PG8_STAGE(PG8_SA(0, 0), a2, voffA);
.LBB0_461:
	s_add_u32 s0, s22, 0x100
	s_addc_u32 s1, s23, 0
	s_cmp_eq_u32 s50, 40
	s_cselect_b32 s27, s19, s1
	s_cselect_b32 s26, s18, s0
	s_cselect_b32 s25, s21, s5
	s_cselect_b32 s24, s20, s4
	s_cmp_eq_u32 s50, 40
	s_cselect_b32 s32, 1, 0
	s_and_b32 s32, s32, s38
	s_add_i32 s6, 0, 0x10000
	s_add_i32 s51, 0, 0x14000
	v_add_u32_e32 v140, s6, v228
	v_add_u32_e32 v156, s51, v228
	ds_read_b128 v[128:131], v140
	ds_read_b128 v[132:135], v140 offset:1024
	ds_read_b128 v[136:139], v140 offset:2048
	ds_read_b128 v[140:143], v140 offset:3072
	ds_read_b128 v[144:147], v156
	ds_read_b128 v[148:151], v156 offset:1024
	ds_read_b128 v[152:155], v156 offset:2048
	ds_read_b128 v[156:159], v156 offset:3072
	s_add_u32 s98, s22, 0xb0080
	s_addc_u32 s99, s23, 0
	s_add_i32 m0, s30, 0xc000
	ds_read_b128 v[160:163], v230
	ds_read_b128 v[164:167], v230 offset:1024
	ds_read_b128 v[168:171], v230 offset:2048
	ds_read_b128 v[172:175], v230 offset:3072
	ds_read_b128 v[176:179], v230 offset:4096
	ds_read_b128 v[180:183], v230 offset:5120
	ds_read_b128 v[204:207], v230 offset:6144
	ds_read_b128 v[208:211], v230 offset:7168
	ds_read_b128 v[212:215], v249
	ds_read_b128 v[232:235], v249 offset:1024
	global_load_lds_dwordx4 v198, s[98:99]
	s_add_i32 m0, s30, 0xe000
	s_nop 0
	global_load_lds_dwordx4 v196, s[98:99]
	s_waitcnt vmcnt(9)
	s_waitcnt lgkmcnt(0)
	s_barrier
	s_setprio 1
	s_waitcnt lgkmcnt(0)
	v_mfma_f32_16x16x32_bf16 v[124:127], v[128:131], v[160:163], v[124:127]
	v_mfma_f32_16x16x32_bf16 v[120:123], v[136:139], v[160:163], v[120:123]
	v_mfma_f32_16x16x32_bf16 v[108:111], v[128:131], v[168:171], v[108:111]
	v_mfma_f32_16x16x32_bf16 v[104:107], v[136:139], v[168:171], v[104:107]
	v_mfma_f32_16x16x32_bf16 v[92:95], v[128:131], v[176:179], v[92:95]
	v_mfma_f32_16x16x32_bf16 v[88:91], v[136:139], v[176:179], v[88:91]
	v_mfma_f32_16x16x32_bf16 v[76:79], v[128:131], v[204:207], v[76:79]
	v_mfma_f32_16x16x32_bf16 v[72:75], v[136:139], v[204:207], v[72:75]
	v_mfma_f32_16x16x32_bf16 v[124:127], v[132:135], v[164:167], v[124:127]
	v_mfma_f32_16x16x32_bf16 v[120:123], v[140:143], v[164:167], v[120:123]
	v_mfma_f32_16x16x32_bf16 v[108:111], v[132:135], v[172:175], v[108:111]
	v_mfma_f32_16x16x32_bf16 v[104:107], v[140:143], v[172:175], v[104:107]
	v_mfma_f32_16x16x32_bf16 v[92:95], v[132:135], v[180:183], v[92:95]
	v_mfma_f32_16x16x32_bf16 v[88:91], v[140:143], v[180:183], v[88:91]
	v_mfma_f32_16x16x32_bf16 v[76:79], v[132:135], v[208:211], v[76:79]
	v_mfma_f32_16x16x32_bf16 v[72:75], v[140:143], v[208:211], v[72:75]
	s_setprio 0
	s_setprio 1
	v_mfma_f32_16x16x32_bf16 v[116:119], v[144:147], v[160:163], v[116:119]
	v_mfma_f32_16x16x32_bf16 v[112:115], v[152:155], v[160:163], v[112:115]
	v_mfma_f32_16x16x32_bf16 v[100:103], v[144:147], v[168:171], v[100:103]
	v_mfma_f32_16x16x32_bf16 v[96:99], v[152:155], v[168:171], v[96:99]
	v_mfma_f32_16x16x32_bf16 v[84:87], v[144:147], v[176:179], v[84:87]
	v_mfma_f32_16x16x32_bf16 v[80:83], v[152:155], v[176:179], v[80:83]
	v_mfma_f32_16x16x32_bf16 v[68:71], v[144:147], v[204:207], v[68:71]
	v_mfma_f32_16x16x32_bf16 v[64:67], v[152:155], v[204:207], v[64:67]
	v_mfma_f32_16x16x32_bf16 v[116:119], v[148:151], v[164:167], v[116:119]
	v_mfma_f32_16x16x32_bf16 v[112:115], v[156:159], v[164:167], v[112:115]
	v_mfma_f32_16x16x32_bf16 v[100:103], v[148:151], v[172:175], v[100:103]
	v_mfma_f32_16x16x32_bf16 v[96:99], v[156:159], v[172:175], v[96:99]
	v_mfma_f32_16x16x32_bf16 v[84:87], v[148:151], v[180:183], v[84:87]
	v_mfma_f32_16x16x32_bf16 v[80:83], v[156:159], v[180:183], v[80:83]
	v_mfma_f32_16x16x32_bf16 v[68:71], v[148:151], v[208:211], v[68:71]
	v_mfma_f32_16x16x32_bf16 v[64:67], v[156:159], v[208:211], v[64:67]
	v_mfma_f32_16x16x32_bf16 v[236:239], v[128:131], v[212:215], v[236:239]
	v_mfma_f32_16x16x32_bf16 v[240:243], v[136:139], v[212:215], v[240:243]
	v_mfma_f32_16x16x32_bf16 v[244:247], v[144:147], v[212:215], v[244:247]
	v_mfma_f32_16x16x32_bf16 v[200:203], v[152:155], v[212:215], v[200:203]
	v_mfma_f32_16x16x32_bf16 v[236:239], v[132:135], v[232:235], v[236:239]
	v_mfma_f32_16x16x32_bf16 v[240:243], v[140:143], v[232:235], v[240:243]
	v_mfma_f32_16x16x32_bf16 v[244:247], v[148:151], v[232:235], v[244:247]
	v_mfma_f32_16x16x32_bf16 v[200:203], v[156:159], v[232:235], v[200:203]
	s_setprio 0
	s_barrier
	s_add_i32 s6, s6, s29
	s_mov_b32 m0, s6
	ds_read_b128 v[160:163], v230 offset:16384
	ds_read_b128 v[164:167], v230 offset:17408
	ds_read_b128 v[168:171], v230 offset:18432
	ds_read_b128 v[172:175], v230 offset:19456
	ds_read_b128 v[176:179], v230 offset:20480
	ds_read_b128 v[180:183], v230 offset:21504
	ds_read_b128 v[204:207], v230 offset:22528
	ds_read_b128 v[208:211], v230 offset:23552
	s_cmp_eq_u32 s32, 1
	s_cbranch_scc1 .Ldn_w1
	global_load_lds_dwordx4 v184, s[24:25]
	s_add_i32 m0, s6, 0x2000
	s_add_u32 s22, s24, 0xb0000
	s_addc_u32 s23, s25, 0
	s_add_i32 s6, s51, s29
	global_load_lds_dwordx4 v194, s[24:25]
	s_mov_b32 m0, s6
	s_nop 0
	global_load_lds_dwordx4 v184, s[22:23]
	s_add_i32 m0, s6, 0x2000
	s_nop 0
	global_load_lds_dwordx4 v194, s[22:23]
	s_mov_b32 m0, s30
	s_nop 0
	global_load_lds_dwordx4 v198, s[26:27]
	s_mov_b32 m0, s31
	s_nop 0
	global_load_lds_dwordx4 v196, s[26:27]
	s_and_b32 m0, s30, 0xc00
	s_add_i32 m0, m0, 0x20800
	s_nop 0
	global_load_lds_dwordx4 v248, s[26:27]
	s_waitcnt vmcnt(9)
	s_branch .Ldn_j1
; #define PG8_STAGE(bufoff, gbase, voff) do { _Pragma("unroll") for (int _i = 0; _i < 2; ++_i) \
;         __builtin_amdgcn_global_load_lds((const unsigned*)((const char*)(gbase) + (voff)[_i]), (PG8_LAS unsigned*)(lds + (bufoff) + ldsw + _i * 8192), 16, 0, 0); } while (0)
; #define PG8_LDA(dst, b, h) do { _Pragma("unroll") for (int m = 0; m < 4; ++m) _Pragma("unroll") for (int k = 0; k < 2; ++k) dst[m][k] = *(const PG8_LAS bf16x8*)(lds + PG8_SA(b, h) + aoff + m * 2048 + k * 1024); } while (0)
; #define PG8_LDB(dst, b, h) do { _Pragma("unroll") for (int n = 0; n < 2; ++n) _Pragma("unroll") for (int k = 0; k < 2; ++k) dst[n][k] = *(const PG8_LAS bf16x8*)(lds + PG8_SB(b, h) + boff + n * 2048 + k * 1024); } while (0)
; #define PG8_MMA(ai, bj, At, Bt) do { __builtin_amdgcn_s_setprio(1); _Pragma("unroll") for (int m = 0; m < 4; ++m) _Pragma("unroll") for (int n = 0; n < 2; ++n) _Pragma("unroll") for (int k = 0; k < 2; ++k) \
;         acc[ai][bj][m][n] = __builtin_amdgcn_mfma_f32_16x16x32_bf16(Bt[n][k], At[m][k], acc[ai][bj][m][n], 0, 0, 0); __builtin_amdgcn_s_setprio(0); } while (0)
; #define PG8_WAIT_V(n) asm volatile("s_waitcnt vmcnt(" #n ")" ::: "memory")
; #define PG8_WAIT_L(n) asm volatile("s_waitcnt lgkmcnt(" #n ")" ::: "memory")
; #define PG8_BAR __builtin_amdgcn_s_barrier()
; #define PG8_SCHED __builtin_amdgcn_sched_barrier(0)
; template <class Epi, class Sched, bool ALIGN_EPI = false, bool SP2 = false>
; __device__ __forceinline__ void gemm_phase(PG8_LAS unsigned char* lds, const Gemm g, const Sched& S, const Epi& E) {
;     ...
;             PG8_WAIT_V(8); PG8_WAIT_L(0); PG8_BAR; PG8_MMA(0, 0, At, B0); PG8_MMA(0, 1, At, B1); PG8_BAR; PG8_SCHED;
;             PG8_LDA(At, 0, 1); PG8_STAGE(PG8_SB(0, 0), b2, voffB); PG8_STAGE(PG8_SB(0, 1), b2 + hstep, voffB); PG8_STAGE(PG8_SA(0, 0), a2, voffA);
;             PG8_WAIT_V(8); PG8_WAIT_L(0); PG8_BAR; PG8_MMA(1, 0, At, B0); PG8_MMA(1, 1, At, B1); PG8_BAR; PG8_SCHED;
;             PG8_LDB(B0, 1, 0); PG8_LDB(B1, 1, 1); PG8_SCHED; PG8_LDA(At, 1, 0); PG8_STAGE(PG8_SA(0, 1), a2 + hstep, voffA);
;             PG8_WAIT_V(8); PG8_WAIT_L(0); PG8_BAR; PG8_MMA(0, 0, At, B0); PG8_MMA(0, 1, At, B1); PG8_BAR; PG8_SCHED;
.Ldn_w1:
	s_waitcnt vmcnt(2)
.Ldn_j1:
	s_waitcnt lgkmcnt(0)
	s_barrier
	s_setprio 1
	s_waitcnt lgkmcnt(0)
	v_mfma_f32_16x16x32_bf16 v[60:63], v[128:131], v[160:163], v[60:63]
	v_mfma_f32_16x16x32_bf16 v[56:59], v[136:139], v[160:163], v[56:59]
	v_mfma_f32_16x16x32_bf16 v[44:47], v[128:131], v[168:171], v[44:47]
	v_mfma_f32_16x16x32_bf16 v[40:43], v[136:139], v[168:171], v[40:43]
	v_mfma_f32_16x16x32_bf16 v[28:31], v[128:131], v[176:179], v[28:31]
	v_mfma_f32_16x16x32_bf16 v[24:27], v[136:139], v[176:179], v[24:27]
	v_mfma_f32_16x16x32_bf16 v[12:15], v[128:131], v[204:207], v[12:15]
	v_mfma_f32_16x16x32_bf16 v[8:11], v[136:139], v[204:207], v[8:11]
	v_mfma_f32_16x16x32_bf16 v[60:63], v[132:135], v[164:167], v[60:63]
	v_mfma_f32_16x16x32_bf16 v[56:59], v[140:143], v[164:167], v[56:59]
	v_mfma_f32_16x16x32_bf16 v[44:47], v[132:135], v[172:175], v[44:47]
	v_mfma_f32_16x16x32_bf16 v[40:43], v[140:143], v[172:175], v[40:43]
	v_mfma_f32_16x16x32_bf16 v[28:31], v[132:135], v[180:183], v[28:31]
	v_mfma_f32_16x16x32_bf16 v[24:27], v[140:143], v[180:183], v[24:27]
	v_mfma_f32_16x16x32_bf16 v[12:15], v[132:135], v[208:211], v[12:15]
	v_mfma_f32_16x16x32_bf16 v[8:11], v[140:143], v[208:211], v[8:11]
	s_setprio 0
	s_setprio 1
	v_mfma_f32_16x16x32_bf16 v[52:55], v[144:147], v[160:163], v[52:55]
	v_mfma_f32_16x16x32_bf16 v[48:51], v[152:155], v[160:163], v[48:51]
	v_mfma_f32_16x16x32_bf16 v[36:39], v[144:147], v[168:171], v[36:39]
	v_mfma_f32_16x16x32_bf16 v[32:35], v[152:155], v[168:171], v[32:35]
	v_mfma_f32_16x16x32_bf16 v[20:23], v[144:147], v[176:179], v[20:23]
	v_mfma_f32_16x16x32_bf16 v[16:19], v[152:155], v[176:179], v[16:19]
	v_mfma_f32_16x16x32_bf16 v[4:7], v[144:147], v[204:207], v[4:7]
	v_mfma_f32_16x16x32_bf16 v[0:3], v[152:155], v[204:207], v[0:3]
	v_mfma_f32_16x16x32_bf16 v[52:55], v[148:151], v[164:167], v[52:55]
	v_mfma_f32_16x16x32_bf16 v[48:51], v[156:159], v[164:167], v[48:51]
	v_mfma_f32_16x16x32_bf16 v[36:39], v[148:151], v[172:175], v[36:39]
	v_mfma_f32_16x16x32_bf16 v[32:35], v[156:159], v[172:175], v[32:35]
	v_mfma_f32_16x16x32_bf16 v[20:23], v[148:151], v[180:183], v[20:23]
	v_mfma_f32_16x16x32_bf16 v[16:19], v[156:159], v[180:183], v[16:19]
	v_mfma_f32_16x16x32_bf16 v[4:7], v[148:151], v[208:211], v[4:7]
	v_mfma_f32_16x16x32_bf16 v[0:3], v[156:159], v[208:211], v[0:3]
	s_setprio 0
	s_barrier
	s_add_i32 s6, 0, 0x18000
	s_add_i32 s51, 0, 0x1c000
	v_add_u32_e32 v140, s6, v228
	v_add_u32_e32 v156, s51, v228
	ds_read_b128 v[128:131], v140
	ds_read_b128 v[132:135], v140 offset:1024
	ds_read_b128 v[136:139], v140 offset:2048
	ds_read_b128 v[140:143], v140 offset:3072
	ds_read_b128 v[144:147], v156
	ds_read_b128 v[148:151], v156 offset:1024
	ds_read_b128 v[152:155], v156 offset:2048
	ds_read_b128 v[156:159], v156 offset:3072
	s_add_u32 s22, s26, 0xb0000
	s_addc_u32 s23, s27, 0
	s_mov_b32 m0, s34
	ds_read_b128 v[160:163], v230 offset:32768
	ds_read_b128 v[164:167], v230 offset:33792
	ds_read_b128 v[168:171], v230 offset:34816
	ds_read_b128 v[172:175], v230 offset:35840
	ds_read_b128 v[176:179], v230 offset:36864
	ds_read_b128 v[180:183], v230 offset:37888
	ds_read_b128 v[204:207], v230 offset:38912
	ds_read_b128 v[208:211], v230 offset:39936
	ds_read_b128 v[212:215], v249 offset:4096
	ds_read_b128 v[232:235], v249 offset:5120
	s_cmp_eq_u32 s32, 1
	s_cbranch_scc1 .Ldn_w2
	global_load_lds_dwordx4 v198, s[22:23]
	s_mov_b32 m0, s40
	s_nop 0
	global_load_lds_dwordx4 v196, s[22:23]
	s_waitcnt vmcnt(9)
	s_branch .Ldn_j2

; #define PG8_STAGE(bufoff, gbase, voff) do { _Pragma("unroll") for (int _i = 0; _i < 2; ++_i) \
;         __builtin_amdgcn_global_load_lds((const unsigned*)((const char*)(gbase) + (voff)[_i]), (PG8_LAS unsigned*)(lds + (bufoff) + ldsw + _i * 8192), 16, 0, 0); } while (0)
; #define PG8_LDA(dst, b, h) do { _Pragma("unroll") for (int m = 0; m < 4; ++m) _Pragma("unroll") for (int k = 0; k < 2; ++k) dst[m][k] = *(const PG8_LAS bf16x8*)(lds + PG8_SA(b, h) + aoff + m * 2048 + k * 1024); } while (0)
; #define PG8_LDB(dst, b, h) do { _Pragma("unroll") for (int n = 0; n < 2; ++n) _Pragma("unroll") for (int k = 0; k < 2; ++k) dst[n][k] = *(const PG8_LAS bf16x8*)(lds + PG8_SB(b, h) + boff + n * 2048 + k * 1024); } while (0)
; #define PG8_MMA(ai, bj, At, Bt) do { __builtin_amdgcn_s_setprio(1); _Pragma("unroll") for (int m = 0; m < 4; ++m) _Pragma("unroll") for (int n = 0; n < 2; ++n) _Pragma("unroll") for (int k = 0; k < 2; ++k) \
;         acc[ai][bj][m][n] = __builtin_amdgcn_mfma_f32_16x16x32_bf16(Bt[n][k], At[m][k], acc[ai][bj][m][n], 0, 0, 0); __builtin_amdgcn_s_setprio(0); } while (0)
; #define PG8_WAIT_V(n) asm volatile("s_waitcnt vmcnt(" #n ")" ::: "memory")
; #define PG8_WAIT_L(n) asm volatile("s_waitcnt lgkmcnt(" #n ")" ::: "memory")
; #define PG8_BAR __builtin_amdgcn_s_barrier()
; #define PG8_SCHED __builtin_amdgcn_sched_barrier(0)
; template <class Epi, class Sched, bool ALIGN_EPI = false, bool SP2 = false>
; __device__ __forceinline__ void gemm_phase(PG8_LAS unsigned char* lds, const Gemm g, const Sched& S, const Epi& E) {
;     ...
;             PG8_WAIT_V(8); PG8_WAIT_L(0); PG8_BAR; PG8_MMA(1, 0, At, B0); PG8_MMA(1, 1, At, B1); PG8_BAR; PG8_SCHED;
;             PG8_LDB(B0, 1, 0); PG8_LDB(B1, 1, 1); PG8_SCHED; PG8_LDA(At, 1, 0); PG8_STAGE(PG8_SA(0, 1), a2 + hstep, voffA);
;             PG8_WAIT_V(8); PG8_WAIT_L(0); PG8_BAR; PG8_MMA(0, 0, At, B0); PG8_MMA(0, 1, At, B1); PG8_BAR; PG8_SCHED;
;             PG8_LDA(At, 1, 1); PG8_STAGE(PG8_SB(1, 0), b3, voffB); PG8_STAGE(PG8_SB(1, 1), b3 + hstep, voffB); PG8_STAGE(PG8_SA(1, 0), a3, voffA);
.Ldn_j2:
	s_waitcnt lgkmcnt(0)
	s_barrier
	s_setprio 1
	s_waitcnt lgkmcnt(0)
	v_mfma_f32_16x16x32_bf16 v[124:127], v[128:131], v[160:163], v[124:127]
	v_mfma_f32_16x16x32_bf16 v[120:123], v[136:139], v[160:163], v[120:123]
	v_mfma_f32_16x16x32_bf16 v[108:111], v[128:131], v[168:171], v[108:111]
	v_mfma_f32_16x16x32_bf16 v[104:107], v[136:139], v[168:171], v[104:107]
	v_mfma_f32_16x16x32_bf16 v[92:95], v[128:131], v[176:179], v[92:95]
	v_mfma_f32_16x16x32_bf16 v[88:91], v[136:139], v[176:179], v[88:91]
	v_mfma_f32_16x16x32_bf16 v[76:79], v[128:131], v[204:207], v[76:79]
	v_mfma_f32_16x16x32_bf16 v[72:75], v[136:139], v[204:207], v[72:75]
	v_mfma_f32_16x16x32_bf16 v[124:127], v[132:135], v[164:167], v[124:127]
	v_mfma_f32_16x16x32_bf16 v[120:123], v[140:143], v[164:167], v[120:123]
	v_mfma_f32_16x16x32_bf16 v[108:111], v[132:135], v[172:175], v[108:111]
	v_mfma_f32_16x16x32_bf16 v[104:107], v[140:143], v[172:175], v[104:107]
	v_mfma_f32_16x16x32_bf16 v[92:95], v[132:135], v[180:183], v[92:95]
	v_mfma_f32_16x16x32_bf16 v[88:91], v[140:143], v[180:183], v[88:91]
	v_mfma_f32_16x16x32_bf16 v[76:79], v[132:135], v[208:211], v[76:79]
	v_mfma_f32_16x16x32_bf16 v[72:75], v[140:143], v[208:211], v[72:75]
	s_setprio 0
	s_setprio 1
	v_mfma_f32_16x16x32_bf16 v[116:119], v[144:147], v[160:163], v[116:119]
	v_mfma_f32_16x16x32_bf16 v[112:115], v[152:155], v[160:163], v[112:115]
	v_mfma_f32_16x16x32_bf16 v[100:103], v[144:147], v[168:171], v[100:103]
	v_mfma_f32_16x16x32_bf16 v[96:99], v[152:155], v[168:171], v[96:99]
	v_mfma_f32_16x16x32_bf16 v[84:87], v[144:147], v[176:179], v[84:87]
	v_mfma_f32_16x16x32_bf16 v[80:83], v[152:155], v[176:179], v[80:83]
	v_mfma_f32_16x16x32_bf16 v[68:71], v[144:147], v[204:207], v[68:71]
	v_mfma_f32_16x16x32_bf16 v[64:67], v[152:155], v[204:207], v[64:67]
	v_mfma_f32_16x16x32_bf16 v[116:119], v[148:151], v[164:167], v[116:119]
	v_mfma_f32_16x16x32_bf16 v[112:115], v[156:159], v[164:167], v[112:115]
	v_mfma_f32_16x16x32_bf16 v[100:103], v[148:151], v[172:175], v[100:103]
	v_mfma_f32_16x16x32_bf16 v[96:99], v[156:159], v[172:175], v[96:99]
	v_mfma_f32_16x16x32_bf16 v[84:87], v[148:151], v[180:183], v[84:87]
	v_mfma_f32_16x16x32_bf16 v[80:83], v[156:159], v[180:183], v[80:83]
	v_mfma_f32_16x16x32_bf16 v[68:71], v[148:151], v[208:211], v[68:71]
	v_mfma_f32_16x16x32_bf16 v[64:67], v[156:159], v[208:211], v[64:67]
	v_mfma_f32_16x16x32_bf16 v[236:239], v[128:131], v[212:215], v[236:239]
	v_mfma_f32_16x16x32_bf16 v[240:243], v[136:139], v[212:215], v[240:243]
	v_mfma_f32_16x16x32_bf16 v[244:247], v[144:147], v[212:215], v[244:247]
	v_mfma_f32_16x16x32_bf16 v[200:203], v[152:155], v[212:215], v[200:203]
	v_mfma_f32_16x16x32_bf16 v[236:239], v[132:135], v[232:235], v[236:239]
	v_mfma_f32_16x16x32_bf16 v[240:243], v[140:143], v[232:235], v[240:243]
	v_mfma_f32_16x16x32_bf16 v[244:247], v[148:151], v[232:235], v[244:247]
	v_mfma_f32_16x16x32_bf16 v[200:203], v[156:159], v[232:235], v[200:203]
	s_setprio 0
	s_barrier
	s_add_i32 s22, s6, s29
	s_add_u32 s98, s24, 0x80
	s_addc_u32 s99, s25, 0
	s_mov_b32 m0, s22
	ds_read_b128 v[160:163], v230 offset:49152
	ds_read_b128 v[164:167], v230 offset:50176
	ds_read_b128 v[168:171], v230 offset:51200
	ds_read_b128 v[172:175], v230 offset:52224
	ds_read_b128 v[176:179], v230 offset:53248
	ds_read_b128 v[180:183], v230 offset:54272
	ds_read_b128 v[204:207], v230 offset:55296
	ds_read_b128 v[208:211], v230 offset:56320
	s_cmp_eq_u32 s32, 1
	s_cbranch_scc1 .Ldn_w3
	global_load_lds_dwordx4 v184, s[98:99]
	s_add_i32 m0, s22, 0x2000
	s_add_u32 s100, s24, 0xb0080
	s_addc_u32 s101, s25, 0
	s_add_i32 s22, s51, s29
	global_load_lds_dwordx4 v194, s[98:99]
	s_mov_b32 m0, s22
	s_add_u32 s98, s26, 0x80
	s_addc_u32 s99, s27, 0
	global_load_lds_dwordx4 v184, s[100:101]
	s_add_i32 m0, s22, 0x2000
	s_nop 0
	global_load_lds_dwordx4 v194, s[100:101]
	s_mov_b32 m0, s41
	s_nop 0
	global_load_lds_dwordx4 v198, s[98:99]
	s_mov_b32 m0, s42
	s_nop 0
	global_load_lds_dwordx4 v196, s[98:99]
	s_and_b32 m0, s30, 0xc00
	s_add_i32 m0, m0, 0x21800
	s_nop 0
	global_load_lds_dwordx4 v248, s[98:99]
	s_waitcnt vmcnt(9)
	s_branch .Ldn_j3

; #define PG8_STAGE(bufoff, gbase, voff) do { _Pragma("unroll") for (int _i = 0; _i < 2; ++_i) \
;         __builtin_amdgcn_global_load_lds((const unsigned*)((const char*)(gbase) + (voff)[_i]), (PG8_LAS unsigned*)(lds + (bufoff) + ldsw + _i * 8192), 16, 0, 0); } while (0)
; #define PG8_LDA(dst, b, h) do { _Pragma("unroll") for (int m = 0; m < 4; ++m) _Pragma("unroll") for (int k = 0; k < 2; ++k) dst[m][k] = *(const PG8_LAS bf16x8*)(lds + PG8_SA(b, h) + aoff + m * 2048 + k * 1024); } while (0)
; #define PG8_MMA(ai, bj, At, Bt) do { __builtin_amdgcn_s_setprio(1); _Pragma("unroll") for (int m = 0; m < 4; ++m) _Pragma("unroll") for (int n = 0; n < 2; ++n) _Pragma("unroll") for (int k = 0; k < 2; ++k) \
;         acc[ai][bj][m][n] = __builtin_amdgcn_mfma_f32_16x16x32_bf16(Bt[n][k], At[m][k], acc[ai][bj][m][n], 0, 0, 0); __builtin_amdgcn_s_setprio(0); } while (0)
; #define PG8_WAIT_V(n) asm volatile("s_waitcnt vmcnt(" #n ")" ::: "memory")
; #define PG8_WAIT_L(n) asm volatile("s_waitcnt lgkmcnt(" #n ")" ::: "memory")
; #define PG8_BAR __builtin_amdgcn_s_barrier()
; #define PG8_SCHED __builtin_amdgcn_sched_barrier(0)
; template <class Epi, class Sched, bool ALIGN_EPI = false, bool SP2 = false>
; __device__ __forceinline__ void gemm_phase(PG8_LAS unsigned char* lds, const Gemm g, const Sched& S, const Epi& E) {
;     ...
;             PG8_WAIT_V(8); PG8_WAIT_L(0); PG8_BAR; PG8_MMA(0, 0, At, B0); PG8_MMA(0, 1, At, B1); PG8_BAR; PG8_SCHED;
;             PG8_LDA(At, 1, 1); PG8_STAGE(PG8_SB(1, 0), b3, voffB); PG8_STAGE(PG8_SB(1, 1), b3 + hstep, voffB); PG8_STAGE(PG8_SA(1, 0), a3, voffA);
;             PG8_WAIT_V(8); PG8_WAIT_L(0); PG8_BAR; PG8_MMA(1, 0, At, B0); PG8_MMA(1, 1, At, B1); PG8_BAR; PG8_SCHED;
.Ldn_j3:
	s_waitcnt lgkmcnt(0)
	s_barrier
	s_setprio 1
	s_waitcnt lgkmcnt(0)
	v_mfma_f32_16x16x32_bf16 v[60:63], v[128:131], v[160:163], v[60:63]
	v_mfma_f32_16x16x32_bf16 v[56:59], v[136:139], v[160:163], v[56:59]
	v_mfma_f32_16x16x32_bf16 v[44:47], v[128:131], v[168:171], v[44:47]
	v_mfma_f32_16x16x32_bf16 v[40:43], v[136:139], v[168:171], v[40:43]
	v_mfma_f32_16x16x32_bf16 v[28:31], v[128:131], v[176:179], v[28:31]
	v_mfma_f32_16x16x32_bf16 v[24:27], v[136:139], v[176:179], v[24:27]
	v_mfma_f32_16x16x32_bf16 v[12:15], v[128:131], v[204:207], v[12:15]
	v_mfma_f32_16x16x32_bf16 v[8:11], v[136:139], v[204:207], v[8:11]
	v_mfma_f32_16x16x32_bf16 v[60:63], v[132:135], v[164:167], v[60:63]
	v_mfma_f32_16x16x32_bf16 v[56:59], v[140:143], v[164:167], v[56:59]
	v_mfma_f32_16x16x32_bf16 v[44:47], v[132:135], v[172:175], v[44:47]
	v_mfma_f32_16x16x32_bf16 v[40:43], v[140:143], v[172:175], v[40:43]
	v_mfma_f32_16x16x32_bf16 v[28:31], v[132:135], v[180:183], v[28:31]
	v_mfma_f32_16x16x32_bf16 v[24:27], v[140:143], v[180:183], v[24:27]
	v_mfma_f32_16x16x32_bf16 v[12:15], v[132:135], v[208:211], v[12:15]
	v_mfma_f32_16x16x32_bf16 v[8:11], v[140:143], v[208:211], v[8:11]
	s_setprio 0
	s_setprio 1
	v_mfma_f32_16x16x32_bf16 v[52:55], v[144:147], v[160:163], v[52:55]
	v_mfma_f32_16x16x32_bf16 v[48:51], v[152:155], v[160:163], v[48:51]
	v_mfma_f32_16x16x32_bf16 v[36:39], v[144:147], v[168:171], v[36:39]
	v_mfma_f32_16x16x32_bf16 v[32:35], v[152:155], v[168:171], v[32:35]
	v_mfma_f32_16x16x32_bf16 v[20:23], v[144:147], v[176:179], v[20:23]
	v_mfma_f32_16x16x32_bf16 v[16:19], v[152:155], v[176:179], v[16:19]
	v_mfma_f32_16x16x32_bf16 v[4:7], v[144:147], v[204:207], v[4:7]
	v_mfma_f32_16x16x32_bf16 v[0:3], v[152:155], v[204:207], v[0:3]
	v_mfma_f32_16x16x32_bf16 v[52:55], v[148:151], v[164:167], v[52:55]
	v_mfma_f32_16x16x32_bf16 v[48:51], v[156:159], v[164:167], v[48:51]
	v_mfma_f32_16x16x32_bf16 v[36:39], v[148:151], v[172:175], v[36:39]
	v_mfma_f32_16x16x32_bf16 v[32:35], v[156:159], v[172:175], v[32:35]
	v_mfma_f32_16x16x32_bf16 v[20:23], v[148:151], v[180:183], v[20:23]
	v_mfma_f32_16x16x32_bf16 v[16:19], v[156:159], v[180:183], v[16:19]
	v_mfma_f32_16x16x32_bf16 v[4:7], v[148:151], v[208:211], v[4:7]
	v_mfma_f32_16x16x32_bf16 v[0:3], v[156:159], v[208:211], v[0:3]
	s_setprio 0
	s_barrier
	s_add_i32 s50, s50, 2
	s_add_u32 s4, s4, 0x100
	s_addc_u32 s5, s5, 0
	s_cmp_gt_u32 s50, 41
	s_mov_b64 s[22:23], s[0:1]
	s_cbranch_scc0 .LBB0_461
	s_and_b64 vcc, exec, s[16:17]
	s_cbranch_vccz .LBB0_464
	s_barrier
